# removed cooperative-groups grid.sync at kernel entry
# baseline (speedup 1.0000x reference)
; __device__ __forceinline__ int hw_lane() { int l = (int)__builtin_amdgcn_mbcnt_hi(~0u, __builtin_amdgcn_mbcnt_lo(~0u, 0u)); asm volatile("" : "+v"(l)); return l; }
; #define LAS __attribute__((address_space(3)))
; __device__ __forceinline__ gptr_t opq_ptr(const void* p) { gptr_t g = (gptr_t)p; asm volatile("" : "+s"(g)); return g; }
; __global__ void __launch_bounds__(NTHR, 2) hybrid_fwd(Args args) {
;     extern __shared__ __attribute__((aligned(16))) unsigned char lds[];
;     cg::grid_group grid = cg::this_grid();
;     LAS unsigned char* ldsl = (LAS unsigned char*)lds;
;     const int wave = __builtin_amdgcn_readfirstlane((int)threadIdx.x >> 6);
;     grid.sync();
;     const int G = gridDim.x, blk = blockIdx.x;
;     unsigned bar_target = 0;
;     ...
;     unsigned xbar_target = 0;
;     int use_xcd = 0;
;     if (wave == 0 && hw_lane() == 0) __hip_atomic_store((unsigned*)opq_ptr(args.ws) + 2048 + blk, (unsigned)__builtin_amdgcn_s_getreg((3 << 11) | 20) & 0xFu, __ATOMIC_RELAXED, __HIP_MEMORY_SCOPE_AGENT);
_Z10hybrid_fwd4Args:
	s_load_dword s20, s[0:1], 0xb0
	v_and_b32_e32 v1, 0x3ff, v0
	s_nop 1
	v_readfirstlane_b32 s72, v1
	s_waitcnt lgkmcnt(0)
	s_cmp_lt_u32 s72, 64
	s_mov_b32 s33, s20
	s_cselect_b64 s[22:23], -1, 0
	s_cmp_gt_u32 s72, 63
	v_mbcnt_lo_u32_b32 v0, -1, 0
	s_cbranch_scc1 .LBB0_14
	v_mbcnt_hi_u32_b32 v1, -1, v0
	s_nop 0
	v_cmp_eq_u32_e32 vcc, 0, v1
	s_and_saveexec_b64 s[4:5], vcc
	s_cbranch_execz .LBB0_13
	s_load_dwordx2 s[6:7], s[0:1], 0xa8
	s_ashr_i32 s3, s2, 31
	s_lshl_b64 s[8:9], s[2:3], 2
	s_waitcnt lgkmcnt(0)
	s_getreg_b32 s3, hwreg(HW_REG_XCC_ID, 0, 4)
	s_add_u32 s6, s6, s8
	s_addc_u32 s7, s7, s9
	s_and_b32 s3, s3, 15
	v_mov_b32_e32 v1, 0x2000
	v_mov_b32_e32 v2, s3
	global_store_dword v1, v2, s[6:7] sc1
